# lru row prefetch: destination quads pre-zeroed before the lane-masked loads, no vmcnt(0) after each of the 8 row loads at sequence starts
# baseline (speedup 1.0000x reference)
; #define LAS __attribute__((address_space(3)))
; __device__ __forceinline__ float bflo(unsigned w) { return __uint_as_float(w << 16); }
; __device__ __forceinline__ float bfhi(unsigned w) { return __uint_as_float(w & 0xffff0000u); }
; __device__ __forceinline__ u32x4 pack8(f32x4 a, f32x4 b) { u32x4 w; w.x = cvtpk(a[0], a[1]); w.y = cvtpk(a[2], a[3]); w.z = cvtpk(b[0], b[1]); w.w = cvtpk(b[2], b[3]); return w; }
; __device__ __forceinline__ void lru_load_rows(const Params& P, int l, int tile, int r0, int c0, u32x4 (&xr)[2][4]) {
;     const bf16* XR = (const bf16*)(P.ws + WS_XR);
;     const bool samp = tile * 64 >= NPT;
; #pragma unroll
;     for (int j = 0; j < 2; ++j) {
;         const int m = tile * 64 + r0 + 32 * j;
;         const int pos = samp ? ((m - NPT) & 3) : (m % LP);
; #pragma unroll
;         for (int i = 0; i < 4; ++i) {
;             u32x4 v = {0u, 0u, 0u, 0u};
;             if (pos - i >= 0) v = *(const u32x4*)(XR + (size_t)(m - i) * 1024 + c0);
; template <int MODE> __device__ __forceinline__ void lru_phase(const Params& P, LAS unsigned char* lds, int l, int tid_in) {
;     ...
;         if (cur) {
; #pragma unroll
;             for (int j = 0; j < 2; ++j) {
;                 f32x4 a0 = *(const LAS f32x4*)(cwl + 512 + c8 * 8), a1 = *(const LAS f32x4*)(cwl + 512 + c8 * 8 + 4);
; #pragma unroll
;                 for (int i = 0; i < 4; ++i) { const u32x4 xw = xr[j][i]; f32x4 x0, x1; const f32x4 w0 = *(const LAS f32x4*)(cwl + i * 128 + c8 * 8), w1 = *(const LAS f32x4*)(cwl + i * 128 + c8 * 8 + 4);
;                     x0[0] = bflo(xw.x); x0[1] = bfhi(xw.x); x0[2] = bflo(xw.y); x0[3] = bfhi(xw.y); x1[0] = bflo(xw.z); x1[1] = bfhi(xw.z); x1[2] = bflo(xw.w); x1[3] = bfhi(xw.w);
;                     a0 += w0 * x0; a1 += w1 * x1; }
;                 *(LAS u32x4*)(xcb + (r0 + 32 * j) * 136 + c8 * 8) = pack8(a0, a1);
;             }
;             if (tile + tstride < NTILE64) lru_load_rows(P, l, tile + tstride, r0, c0, xr);
.LBB0_1105:
	s_cmpk_lt_u32 s42, 0x10a
	s_cselect_b64 s[4:5], -1, 0
	s_cmp_gt_i32 s12, -1
	s_cselect_b64 s[54:55], -1, 0
	s_or_b64 s[0:1], s[54:55], s[4:5]
	v_cndmask_b32_e64 v0, 0, 1, s[0:1]
	v_cmp_ne_u32_e64 s[46:47], 1, v0
	s_andn2_b64 vcc, exec, s[0:1]
	s_cbranch_vccnz .LBB0_1113
	v_cndmask_b32_e64 v0, 0, 1, s[4:5]
	v_cmp_ne_u32_e64 s[48:49], 1, v0
	s_andn2_b64 vcc, exec, s[4:5]
	s_lshl_b32 s43, s42, 6
	s_cbranch_vccnz .LBB0_1159
	ds_read_b128 v[0:3], v182
	ds_read_b128 v[4:7], v182 offset:16
	ds_read_b128 v[8:11], v183
	ds_read_b128 v[12:15], v183 offset:16
	ds_read_b128 v[24:27], v183 offset:512
	ds_read_b128 v[28:31], v183 offset:528
	s_waitcnt vmcnt(2)
	v_lshlrev_b32_e32 v16, 16, v120
	v_and_b32_e32 v17, 0xffff0000, v120
	v_lshlrev_b32_e32 v18, 16, v121
	v_and_b32_e32 v19, 0xffff0000, v121
	v_lshlrev_b32_e32 v20, 16, v122
	v_and_b32_e32 v21, 0xffff0000, v122
	v_lshlrev_b32_e32 v22, 16, v123
	v_and_b32_e32 v23, 0xffff0000, v123
	s_waitcnt lgkmcnt(2)
	v_pk_fma_f32 v[8:9], v[8:9], v[16:17], v[0:1]
	v_pk_fma_f32 v[10:11], v[10:11], v[18:19], v[2:3]
	v_pk_fma_f32 v[12:13], v[12:13], v[20:21], v[4:5]
	v_pk_fma_f32 v[14:15], v[14:15], v[22:23], v[6:7]
	ds_read_b128 v[0:3], v183 offset:1024
	ds_read_b128 v[4:7], v183 offset:1040
	v_lshlrev_b32_e32 v16, 16, v124
	v_and_b32_e32 v17, 0xffff0000, v124
	v_lshlrev_b32_e32 v18, 16, v125
	v_and_b32_e32 v19, 0xffff0000, v125
	v_lshlrev_b32_e32 v20, 16, v126
	v_and_b32_e32 v21, 0xffff0000, v126
	v_lshlrev_b32_e32 v22, 16, v127
	v_and_b32_e32 v23, 0xffff0000, v127
	s_waitcnt lgkmcnt(2)
	v_pk_fma_f32 v[10:11], v[26:27], v[18:19], v[10:11]
	v_pk_fma_f32 v[8:9], v[24:25], v[16:17], v[8:9]
	v_pk_fma_f32 v[14:15], v[30:31], v[22:23], v[14:15]
	v_pk_fma_f32 v[12:13], v[28:29], v[20:21], v[12:13]
	ds_read_b128 v[24:27], v183 offset:1536
	ds_read_b128 v[28:31], v183 offset:1552
	v_lshlrev_b32_e32 v16, 16, v128
	v_and_b32_e32 v17, 0xffff0000, v128
	v_lshlrev_b32_e32 v18, 16, v129
	v_and_b32_e32 v19, 0xffff0000, v129
	v_lshlrev_b32_e32 v20, 16, v130
	v_and_b32_e32 v21, 0xffff0000, v130
	v_lshlrev_b32_e32 v22, 16, v131
	v_and_b32_e32 v23, 0xffff0000, v131
	s_waitcnt lgkmcnt(2)
	v_pk_fma_f32 v[8:9], v[0:1], v[16:17], v[8:9]
	v_pk_fma_f32 v[10:11], v[2:3], v[18:19], v[10:11]
	v_pk_fma_f32 v[12:13], v[4:5], v[20:21], v[12:13]
	v_pk_fma_f32 v[14:15], v[6:7], v[22:23], v[14:15]
	v_lshlrev_b32_e32 v16, 16, v132
	v_and_b32_e32 v17, 0xffff0000, v132
	v_lshlrev_b32_e32 v18, 16, v133
	v_and_b32_e32 v19, 0xffff0000, v133
	v_lshlrev_b32_e32 v20, 16, v134
	v_and_b32_e32 v21, 0xffff0000, v134
	v_lshlrev_b32_e32 v22, 16, v135
	v_and_b32_e32 v23, 0xffff0000, v135
	s_waitcnt lgkmcnt(0)
	v_pk_fma_f32 v[2:3], v[26:27], v[18:19], v[10:11]
	v_pk_fma_f32 v[0:1], v[24:25], v[16:17], v[8:9]
	v_pk_fma_f32 v[6:7], v[30:31], v[22:23], v[14:15]
	v_pk_fma_f32 v[4:5], v[28:29], v[20:21], v[12:13]
	v_cvt_pk_bf16_f32 v0, v0, v1
	v_cvt_pk_bf16_f32 v1, v2, v3
	v_cvt_pk_bf16_f32 v2, v4, v5
	v_cvt_pk_bf16_f32 v3, v6, v7
	ds_write_b128 v238, v[0:3]
	ds_read_b128 v[0:3], v182
	ds_read_b128 v[4:7], v182 offset:16
	ds_read_b128 v[8:11], v183
	ds_read_b128 v[12:15], v183 offset:16
	ds_read_b128 v[24:27], v183 offset:512
	ds_read_b128 v[28:31], v183 offset:528
	v_lshlrev_b32_e32 v16, 16, v136
	v_and_b32_e32 v17, 0xffff0000, v136
	v_lshlrev_b32_e32 v18, 16, v137
	v_and_b32_e32 v19, 0xffff0000, v137
	v_lshlrev_b32_e32 v20, 16, v138
	v_and_b32_e32 v21, 0xffff0000, v138
	v_lshlrev_b32_e32 v22, 16, v139
	v_and_b32_e32 v23, 0xffff0000, v139
	s_waitcnt lgkmcnt(2)
	v_pk_fma_f32 v[8:9], v[8:9], v[16:17], v[0:1]
	v_pk_fma_f32 v[10:11], v[10:11], v[18:19], v[2:3]
	v_pk_fma_f32 v[12:13], v[12:13], v[20:21], v[4:5]
	v_pk_fma_f32 v[14:15], v[14:15], v[22:23], v[6:7]
	ds_read_b128 v[0:3], v183 offset:1024
	ds_read_b128 v[4:7], v183 offset:1040
	v_lshlrev_b32_e32 v16, 16, v140
	v_and_b32_e32 v17, 0xffff0000, v140
	v_lshlrev_b32_e32 v18, 16, v141
	v_and_b32_e32 v19, 0xffff0000, v141
	v_lshlrev_b32_e32 v20, 16, v142
	v_and_b32_e32 v21, 0xffff0000, v142
	v_lshlrev_b32_e32 v22, 16, v143
	v_and_b32_e32 v23, 0xffff0000, v143
	s_waitcnt lgkmcnt(2)
	v_pk_fma_f32 v[10:11], v[26:27], v[18:19], v[10:11]
	v_pk_fma_f32 v[8:9], v[24:25], v[16:17], v[8:9]
	v_pk_fma_f32 v[14:15], v[30:31], v[22:23], v[14:15]
	v_pk_fma_f32 v[12:13], v[28:29], v[20:21], v[12:13]
	ds_read_b128 v[24:27], v183 offset:1536
	ds_read_b128 v[28:31], v183 offset:1552
	v_lshlrev_b32_e32 v16, 16, v144
	v_and_b32_e32 v17, 0xffff0000, v144
	v_lshlrev_b32_e32 v18, 16, v145
	v_and_b32_e32 v19, 0xffff0000, v145
	v_lshlrev_b32_e32 v20, 16, v146
	v_and_b32_e32 v21, 0xffff0000, v146
	v_lshlrev_b32_e32 v22, 16, v147
	v_and_b32_e32 v23, 0xffff0000, v147
	s_waitcnt lgkmcnt(2)
	v_pk_fma_f32 v[8:9], v[0:1], v[16:17], v[8:9]
	v_pk_fma_f32 v[10:11], v[2:3], v[18:19], v[10:11]
	v_pk_fma_f32 v[12:13], v[4:5], v[20:21], v[12:13]
	v_pk_fma_f32 v[14:15], v[6:7], v[22:23], v[14:15]
	v_lshlrev_b32_e32 v16, 16, v148
	v_and_b32_e32 v17, 0xffff0000, v148
	v_lshlrev_b32_e32 v18, 16, v149
	v_and_b32_e32 v19, 0xffff0000, v149
	v_lshlrev_b32_e32 v20, 16, v150
	v_and_b32_e32 v21, 0xffff0000, v150
	v_lshlrev_b32_e32 v22, 16, v151
	v_and_b32_e32 v23, 0xffff0000, v151
	s_waitcnt lgkmcnt(0)
	v_pk_fma_f32 v[2:3], v[26:27], v[18:19], v[10:11]
	v_pk_fma_f32 v[0:1], v[24:25], v[16:17], v[8:9]
	v_pk_fma_f32 v[6:7], v[30:31], v[22:23], v[14:15]
	v_pk_fma_f32 v[4:5], v[28:29], v[20:21], v[12:13]
	v_cvt_pk_bf16_f32 v0, v0, v1
	v_cvt_pk_bf16_f32 v1, v2, v3
	v_cvt_pk_bf16_f32 v2, v4, v5
	v_cvt_pk_bf16_f32 v3, v6, v7
	v_readlane_b32 s0, v255, 32
	s_nop 0
	s_add_i32 s0, s42, s0
	s_cmpk_gt_u32 s0, 0x109
	ds_write_b128 v238, v[0:3] offset:8704
	s_cbranch_scc1 .LBB0_1158
	v_lshl_add_u32 v0, s0, 6, v177
	v_mul_hi_i32 v1, v0, s71
	v_lshrrev_b32_e32 v2, 31, v1
	v_ashrrev_i32_e32 v1, 7, v1
	v_add_u32_e32 v1, v1, v2
	s_cmpk_gt_u32 s0, 0x101
	v_mul_lo_u32 v1, v1, s73
	v_sub_u32_e32 v1, v0, v1
	s_cselect_b64 s[52:53], -1, 0
	v_cndmask_b32_e64 v4, v1, v154, s[52:53]
	v_cmp_lt_i32_e32 vcc, -1, v4
	v_ashrrev_i32_e32 v1, 31, v0
	v_mov_b32_e32 v120, 0
	v_mov_b32_e32 v121, 0
	v_mov_b32_e32 v122, 0
	v_mov_b32_e32 v123, 0
	s_and_saveexec_b64 s[0:1], vcc
	s_xor_b64 s[0:1], exec, s[0:1]
	s_cbranch_execz .LBB0_1110
	v_lshlrev_b64 v[2:3], 11, v[0:1]
	v_lshl_add_u64 v[2:3], v[168:169], 0, v[2:3]
	global_load_dwordx4 v[120:123], v[2:3], off

; __device__ __forceinline__ u32x4 pack8(f32x4 a, f32x4 b) { u32x4 w; w.x = cvtpk(a[0], a[1]); w.y = cvtpk(a[2], a[3]); w.z = cvtpk(b[0], b[1]); w.w = cvtpk(b[2], b[3]); return w; }
; __device__ __forceinline__ void lru_load_rows(const Params& P, int l, int tile, int r0, int c0, u32x4 (&xr)[2][4]) {
;     ...
;     for (int j = 0; j < 2; ++j) {
;         const int m = tile * 64 + r0 + 32 * j;
;         const int pos = samp ? ((m - NPT) & 3) : (m % LP);
; #pragma unroll
;         for (int i = 0; i < 4; ++i) {
;             u32x4 v = {0u, 0u, 0u, 0u};
;             if (pos - i >= 0) v = *(const u32x4*)(XR + (size_t)(m - i) * 1024 + c0);
;             else if (samp) { const float* buf = P.in[I_SC] + ((size_t)((l * 128 + ((m - NPT) >> 2)) * 3) + (3 + pos - i)) * 1024 + c0; v = pack8(*(const f32x4*)buf, *(const f32x4*)(buf + 4)); }
;             xr[j][i] = v;
.LBB0_1115:
	s_or_b64 exec, exec, s[0:1]
	v_cmp_lt_i32_e32 vcc, 0, v4
	v_mov_b32_e32 v124, 0
	v_mov_b32_e32 v125, 0
	v_mov_b32_e32 v126, 0
	v_mov_b32_e32 v127, 0
	s_and_saveexec_b64 s[0:1], vcc
	s_xor_b64 s[0:1], exec, s[0:1]
	s_cbranch_execz .LBB0_1117
	v_lshlrev_b64 v[6:7], 11, v[0:1]
	v_lshl_add_u64 v[6:7], v[168:169], 0, v[6:7]
	global_load_dwordx4 v[124:127], v[6:7], off offset:-2048

; __device__ __forceinline__ u32x4 pack8(f32x4 a, f32x4 b) { u32x4 w; w.x = cvtpk(a[0], a[1]); w.y = cvtpk(a[2], a[3]); w.z = cvtpk(b[0], b[1]); w.w = cvtpk(b[2], b[3]); return w; }
; __device__ __forceinline__ void lru_load_rows(const Params& P, int l, int tile, int r0, int c0, u32x4 (&xr)[2][4]) {
;     ...
;     for (int j = 0; j < 2; ++j) {
;         const int m = tile * 64 + r0 + 32 * j;
;         const int pos = samp ? ((m - NPT) & 3) : (m % LP);
; #pragma unroll
;         for (int i = 0; i < 4; ++i) {
;             u32x4 v = {0u, 0u, 0u, 0u};
;             if (pos - i >= 0) v = *(const u32x4*)(XR + (size_t)(m - i) * 1024 + c0);
;             else if (samp) { const float* buf = P.in[I_SC] + ((size_t)((l * 128 + ((m - NPT) >> 2)) * 3) + (3 + pos - i)) * 1024 + c0; v = pack8(*(const f32x4*)buf, *(const f32x4*)(buf + 4)); }
;             xr[j][i] = v;
.LBB0_1121:
	s_or_b64 exec, exec, s[0:1]
	v_cmp_lt_i32_e32 vcc, 1, v4
	v_mov_b32_e32 v128, 0
	v_mov_b32_e32 v129, 0
	v_mov_b32_e32 v130, 0
	v_mov_b32_e32 v131, 0
	s_and_saveexec_b64 s[0:1], vcc
	s_xor_b64 s[0:1], exec, s[0:1]
	s_cbranch_execz .LBB0_1123
	v_lshlrev_b64 v[6:7], 11, v[0:1]
	v_lshl_add_u64 v[6:7], v[168:169], 0, v[6:7]
	global_load_dwordx4 v[128:131], v[6:7], off offset:-4096

; __device__ __forceinline__ u32x4 pack8(f32x4 a, f32x4 b) { u32x4 w; w.x = cvtpk(a[0], a[1]); w.y = cvtpk(a[2], a[3]); w.z = cvtpk(b[0], b[1]); w.w = cvtpk(b[2], b[3]); return w; }
; __device__ __forceinline__ void lru_load_rows(const Params& P, int l, int tile, int r0, int c0, u32x4 (&xr)[2][4]) {
;     ...
;     for (int j = 0; j < 2; ++j) {
;         const int m = tile * 64 + r0 + 32 * j;
;         const int pos = samp ? ((m - NPT) & 3) : (m % LP);
; #pragma unroll
;         for (int i = 0; i < 4; ++i) {
;             u32x4 v = {0u, 0u, 0u, 0u};
;             if (pos - i >= 0) v = *(const u32x4*)(XR + (size_t)(m - i) * 1024 + c0);
;             else if (samp) { const float* buf = P.in[I_SC] + ((size_t)((l * 128 + ((m - NPT) >> 2)) * 3) + (3 + pos - i)) * 1024 + c0; v = pack8(*(const f32x4*)buf, *(const f32x4*)(buf + 4)); }
;             xr[j][i] = v;
.LBB0_1127:
	s_or_b64 exec, exec, s[0:1]
	v_cmp_lt_i32_e32 vcc, 2, v4
	v_mov_b32_e32 v132, 0
	v_mov_b32_e32 v133, 0
	v_mov_b32_e32 v134, 0
	v_mov_b32_e32 v135, 0
	s_and_saveexec_b64 s[0:1], vcc
	s_xor_b64 s[0:1], exec, s[0:1]
	s_cbranch_execz .LBB0_1129
	v_lshlrev_b64 v[2:3], 11, v[0:1]
	v_lshl_add_u64 v[2:3], v[168:169], 0, v[2:3]
	v_add_co_u32_e32 v2, vcc, 0xfffff000, v2
	s_nop 1
	v_addc_co_u32_e32 v3, vcc, -1, v3, vcc
	global_load_dwordx4 v[132:135], v[2:3], off offset:-2048

; __device__ __forceinline__ u32x4 pack8(f32x4 a, f32x4 b) { u32x4 w; w.x = cvtpk(a[0], a[1]); w.y = cvtpk(a[2], a[3]); w.z = cvtpk(b[0], b[1]); w.w = cvtpk(b[2], b[3]); return w; }
; __device__ __forceinline__ void lru_load_rows(const Params& P, int l, int tile, int r0, int c0, u32x4 (&xr)[2][4]) {
;     ...
;     for (int j = 0; j < 2; ++j) {
;         const int m = tile * 64 + r0 + 32 * j;
;         const int pos = samp ? ((m - NPT) & 3) : (m % LP);
; #pragma unroll
;         for (int i = 0; i < 4; ++i) {
;             u32x4 v = {0u, 0u, 0u, 0u};
;             if (pos - i >= 0) v = *(const u32x4*)(XR + (size_t)(m - i) * 1024 + c0);
;             else if (samp) { const float* buf = P.in[I_SC] + ((size_t)((l * 128 + ((m - NPT) >> 2)) * 3) + (3 + pos - i)) * 1024 + c0; v = pack8(*(const f32x4*)buf, *(const f32x4*)(buf + 4)); }
;             xr[j][i] = v;
.LBB0_1133:
	s_or_b64 exec, exec, s[0:1]
	v_add_u32_e32 v2, 32, v0
	v_mul_hi_i32 v3, v2, s71
	v_lshrrev_b32_e32 v4, 31, v3
	v_ashrrev_i32_e32 v3, 7, v3
	v_add_u32_e32 v3, v3, v4
	v_mul_lo_u32 v3, v3, s73
	v_sub_u32_e32 v3, v2, v3
	v_cndmask_b32_e64 v4, v3, v154, s[52:53]
	v_cmp_lt_i32_e32 vcc, -1, v4
	v_mov_b32_e32 v136, 0
	v_mov_b32_e32 v137, 0
	v_mov_b32_e32 v138, 0
	v_mov_b32_e32 v139, 0
	s_and_saveexec_b64 s[0:1], vcc
	s_xor_b64 s[0:1], exec, s[0:1]
	s_cbranch_execz .LBB0_1135
	v_ashrrev_i32_e32 v3, 31, v2
	v_lshlrev_b64 v[2:3], 11, v[2:3]
	v_lshl_add_u64 v[2:3], v[168:169], 0, v[2:3]
	global_load_dwordx4 v[136:139], v[2:3], off

; __device__ __forceinline__ u32x4 pack8(f32x4 a, f32x4 b) { u32x4 w; w.x = cvtpk(a[0], a[1]); w.y = cvtpk(a[2], a[3]); w.z = cvtpk(b[0], b[1]); w.w = cvtpk(b[2], b[3]); return w; }
; __device__ __forceinline__ void lru_load_rows(const Params& P, int l, int tile, int r0, int c0, u32x4 (&xr)[2][4]) {
;     ...
;     for (int j = 0; j < 2; ++j) {
;         const int m = tile * 64 + r0 + 32 * j;
;         const int pos = samp ? ((m - NPT) & 3) : (m % LP);
; #pragma unroll
;         for (int i = 0; i < 4; ++i) {
;             u32x4 v = {0u, 0u, 0u, 0u};
;             if (pos - i >= 0) v = *(const u32x4*)(XR + (size_t)(m - i) * 1024 + c0);
;             else if (samp) { const float* buf = P.in[I_SC] + ((size_t)((l * 128 + ((m - NPT) >> 2)) * 3) + (3 + pos - i)) * 1024 + c0; v = pack8(*(const f32x4*)buf, *(const f32x4*)(buf + 4)); }
;             xr[j][i] = v;
.LBB0_1139:
	s_or_b64 exec, exec, s[0:1]
	v_cmp_lt_i32_e32 vcc, 0, v4
	v_mov_b32_e32 v140, 0
	v_mov_b32_e32 v141, 0
	v_mov_b32_e32 v142, 0
	v_mov_b32_e32 v143, 0
	s_and_saveexec_b64 s[0:1], vcc
	s_xor_b64 s[0:1], exec, s[0:1]
	s_cbranch_execz .LBB0_1141
	v_lshlrev_b64 v[6:7], 11, v[0:1]
	v_lshl_add_u64 v[6:7], v[168:169], 0, v[6:7]
	v_add_co_u32_e32 v6, vcc, 0xf000, v6
	s_nop 1
	v_addc_co_u32_e32 v7, vcc, 0, v7, vcc
	global_load_dwordx4 v[140:143], v[6:7], off offset:2048

; __device__ __forceinline__ u32x4 pack8(f32x4 a, f32x4 b) { u32x4 w; w.x = cvtpk(a[0], a[1]); w.y = cvtpk(a[2], a[3]); w.z = cvtpk(b[0], b[1]); w.w = cvtpk(b[2], b[3]); return w; }
; __device__ __forceinline__ void lru_load_rows(const Params& P, int l, int tile, int r0, int c0, u32x4 (&xr)[2][4]) {
;     ...
;     for (int j = 0; j < 2; ++j) {
;         const int m = tile * 64 + r0 + 32 * j;
;         const int pos = samp ? ((m - NPT) & 3) : (m % LP);
; #pragma unroll
;         for (int i = 0; i < 4; ++i) {
;             u32x4 v = {0u, 0u, 0u, 0u};
;             if (pos - i >= 0) v = *(const u32x4*)(XR + (size_t)(m - i) * 1024 + c0);
;             else if (samp) { const float* buf = P.in[I_SC] + ((size_t)((l * 128 + ((m - NPT) >> 2)) * 3) + (3 + pos - i)) * 1024 + c0; v = pack8(*(const f32x4*)buf, *(const f32x4*)(buf + 4)); }
;             xr[j][i] = v;
.LBB0_1145:
	s_or_b64 exec, exec, s[0:1]
	v_cmp_lt_i32_e32 vcc, 1, v4
	v_mov_b32_e32 v144, 0
	v_mov_b32_e32 v145, 0
	v_mov_b32_e32 v146, 0
	v_mov_b32_e32 v147, 0
	s_and_saveexec_b64 s[0:1], vcc
	s_xor_b64 s[0:1], exec, s[0:1]
	s_cbranch_execz .LBB0_1147
	v_lshlrev_b64 v[6:7], 11, v[0:1]
	v_lshl_add_u64 v[6:7], v[168:169], 0, v[6:7]
	v_add_co_u32_e32 v6, vcc, 0xf000, v6
	s_nop 1
	v_addc_co_u32_e32 v7, vcc, 0, v7, vcc
	global_load_dwordx4 v[144:147], v[6:7], off

; __device__ __forceinline__ u32x4 pack8(f32x4 a, f32x4 b) { u32x4 w; w.x = cvtpk(a[0], a[1]); w.y = cvtpk(a[2], a[3]); w.z = cvtpk(b[0], b[1]); w.w = cvtpk(b[2], b[3]); return w; }
; __device__ __forceinline__ void lru_load_rows(const Params& P, int l, int tile, int r0, int c0, u32x4 (&xr)[2][4]) {
;     ...
;     for (int j = 0; j < 2; ++j) {
;         const int m = tile * 64 + r0 + 32 * j;
;         const int pos = samp ? ((m - NPT) & 3) : (m % LP);
; #pragma unroll
;         for (int i = 0; i < 4; ++i) {
;             u32x4 v = {0u, 0u, 0u, 0u};
;             if (pos - i >= 0) v = *(const u32x4*)(XR + (size_t)(m - i) * 1024 + c0);
;             else if (samp) { const float* buf = P.in[I_SC] + ((size_t)((l * 128 + ((m - NPT) >> 2)) * 3) + (3 + pos - i)) * 1024 + c0; v = pack8(*(const f32x4*)buf, *(const f32x4*)(buf + 4)); }
;             xr[j][i] = v;
.LBB0_1151:
	s_or_b64 exec, exec, s[0:1]
	v_cmp_lt_i32_e32 vcc, 2, v4
	v_mov_b32_e32 v148, 0
	v_mov_b32_e32 v149, 0
	v_mov_b32_e32 v150, 0
	v_mov_b32_e32 v151, 0
	s_and_saveexec_b64 s[0:1], vcc
	s_xor_b64 s[0:1], exec, s[0:1]
	s_cbranch_execz .LBB0_1153
	v_lshlrev_b64 v[0:1], 11, v[0:1]
	v_lshl_add_u64 v[0:1], v[168:169], 0, v[0:1]
	v_add_co_u32_e32 v0, vcc, 0xe000, v0
	s_nop 1
	v_addc_co_u32_e32 v1, vcc, 0, v1, vcc
	global_load_dwordx4 v[148:151], v[0:1], off offset:2048

; __device__ __forceinline__ u32x4 pack8(f32x4 a, f32x4 b) { u32x4 w; w.x = cvtpk(a[0], a[1]); w.y = cvtpk(a[2], a[3]); w.z = cvtpk(b[0], b[1]); w.w = cvtpk(b[2], b[3]); return w; }
; __device__ __forceinline__ void lru_load_rows(const Params& P, int l, int tile, int r0, int c0, u32x4 (&xr)[2][4]) {
;     ...
;     for (int j = 0; j < 2; ++j) {
;         const int m = tile * 64 + r0 + 32 * j;
;         const int pos = samp ? ((m - NPT) & 3) : (m % LP);
; #pragma unroll
;         for (int i = 0; i < 4; ++i) {
;             u32x4 v = {0u, 0u, 0u, 0u};
;             if (pos - i >= 0) v = *(const u32x4*)(XR + (size_t)(m - i) * 1024 + c0);
;             else if (samp) { const float* buf = P.in[I_SC] + ((size_t)((l * 128 + ((m - NPT) >> 2)) * 3) + (3 + pos - i)) * 1024 + c0; v = pack8(*(const f32x4*)buf, *(const f32x4*)(buf + 4)); }
;             xr[j][i] = v;
.LBB0_1156:
	v_mov_b32_e32 v82, v81
	v_mov_b32_e32 v83, v81
	v_mov_b32_e32 v80, v81
.LBB0_1157:
	s_or_b64 exec, exec, s[0:1]
